# in-proj: per-CU start delay of (CU%8) K-step times so CUs of an XCD are at different K offsets (L2 channel de-camping test)
# speedup vs baseline: 1.0073x; 1.0033x over previous
; __global__ void __launch_bounds__(512, 2) mega(P p) {
;     ...
;   for (int ph = p.pb; ph < p.pe; ++ph) {
;     if (ph == 0) phase_prep(p, lds);
;     else if (ph == 1) phase_h0(p);
;     else {
;       const int l = (ph - 2) >> 2, s = (ph - 2) & 3;
;       if (s == 0) { for (int rr = 0; rr < REP_INPROJ; ++rr) { if (rr) cg::this_grid().sync(); phase_inproj(p, l, lds); } }
.LBB0_74:
	s_andn2_b64 vcc, exec, s[0:1]
	s_cbranch_vccnz .LBB0_941
	s_cmp_lg_u32 s24, 1
	s_mov_b64 s[0:1], -1
	s_cbranch_scc0 .LBB0_812
	v_readlane_b32 s0, v254, 9
	v_readlane_b32 s1, v254, 10
	v_mov_b32_e32 v0, v195
	s_andn2_b64 vcc, exec, s[0:1]
	s_cbranch_vccnz .LBB0_811
	s_and_b32 s100, s84, 7
	s_cmp_eq_u32 s100, 0
	s_cbranch_scc1 .Lkskew_in_done
.Lkskew_in_loop:
	s_sleep 50
	s_sub_i32 s100, s100, 1
	s_cmp_lg_u32 s100, 0
	s_cbranch_scc1 .Lkskew_in_loop
